# stack5: stack4 + ff2 context tiles staged as a 4-slot ring of half K-slices (3 in flight, counted vmcnt)
# speedup vs baseline: 1.0339x; 1.0056x over previous
; #define WAIT_V0() asm volatile("s_waitcnt vmcnt(0)" ::: "memory")
; template <int EK, int TS, int KS>
; DI void ctx_tiles(const Params& p, int l, const bf16_t* __restrict__ A, const bf16_t* __restrict__ Bt, int N, int K, ldsp_t shm) {
;     ...
;         const int tm = u / ntn, tn = u % ntn;
;         int tid = threadIdx.x;
;         asm volatile("" : "+v"(tid));
;         const int wid = tid >> 6, lane = tid & 63, wr = wid >> 2, wc = wid & 3, fr = lane & 15, fq = lane >> 4;
;         unsigned soff[PP];
; #pragma unroll
;         for (int i = 0; i < PP; ++i) { int sR, sC; stage_rc_ks<KS>((wid * PP + i) * 1024 + lane * 16, sR, sC); soff[i] = (unsigned)(sR * K + sC) * 2u; }
;         const bf16_t* Ab = A + (size_t)tm * TS * K;
;         const bf16_t* Bb = Bt + (size_t)tn * TS * K;
;     ...
;         f32x4 acc[MT][NT];
; #pragma unroll
;         for (int m = 0; m < MT; ++m)
; #pragma unroll
;             for (int n = 0; n < NT; ++n) acc[m][n] = (f32x4){0.f, 0.f, 0.f, 0.f};
;         const int aoff = lds_byte_ks<KS>(wr * WM + fr, fq * 8), boff = lds_byte_ks<KS>(wc * WN + fr, fq * 8);
;         C_STAGE(0, 0); WAIT_V0(); __syncthreads();
;         for (int t = 0; t < nt; ++t) {
;             const int cur = t & 1;
;             if (t + 1 < nt) C_STAGE(cur ^ 1, t + 1);
.LBB0_246:
	v_mov_b32_e32 v24, v252
	s_ashr_i32 s4, s44, 31
	v_ashrrev_i32_e32 v0, 6, v24
	v_lshlrev_b32_e32 v29, 12, v0
	v_lshlrev_b32_e32 v3, 11, v24
	s_waitcnt lgkmcnt(0)
	v_and_b32_e32 v5, 0x1e000, v3
	v_ashrrev_i32_e32 v3, 10, v29
	v_lshlrev_b32_e32 v1, 4, v24
	v_and_b32_e32 v4, 32, v24
	v_lshrrev_b32_e32 v6, 29, v3
	v_bitop3_b32 v2, v1, v4, 48 bitop3:0x6c
	v_add_u32_e32 v7, v3, v6
	v_or_b32_e32 v2, v2, v5
	v_ashrrev_i32_e32 v8, 3, v7
	v_and_b32_e32 v7, 0x3fffff8, v7
	v_sub_u32_e32 v7, v3, v7
	v_lshl_or_b32 v9, v8, 17, v2
	v_or_b32_e32 v10, 1, v3
	v_lshl_add_u32 v7, v7, 6, v9
	v_add_u32_e32 v9, v10, v6
	v_ashrrev_i32_e32 v11, 3, v9
	v_and_b32_e32 v9, 0x3fffff8, v9
	v_sub_u32_e32 v9, v10, v9
	v_lshl_or_b32 v12, v11, 17, v2
	v_lshl_add_u32 v9, v9, 6, v12
	v_or_b32_e32 v12, 2, v3
	s_lshr_b32 s4, s4, 28
	v_add_u32_e32 v13, v12, v6
	s_add_i32 s5, s44, s4
	v_ashrrev_i32_e32 v14, 3, v13
	v_and_b32_e32 v13, 0x3fffff8, v13
	s_ashr_i32 s4, s5, 4
	v_sub_u32_e32 v13, v12, v13
	v_lshl_or_b32 v15, v14, 17, v2
	s_and_b32 s5, s5, -16
	v_lshl_add_u32 v13, v13, 6, v15
	v_or_b32_e32 v15, 3, v3
	s_sub_i32 s40, s44, s5
	v_add_u32_e32 v6, v15, v6
	s_ashr_i32 s5, s4, 31
	s_ashr_i32 s41, s40, 31
	v_ashrrev_i32_e32 v16, 3, v6
	v_and_b32_e32 v6, 0x3fffff8, v6
	s_lshl_b64 s[42:43], s[4:5], 19
	s_lshl_b64 s[46:47], s[40:41], 19
	v_sub_u32_e32 v6, v15, v6
	v_lshl_or_b32 v2, v16, 17, v2
	s_add_u32 s50, s87, s42
	v_lshl_add_u32 v2, v6, 6, v2
	s_addc_u32 s51, s90, s43
	v_lshrrev_b32_e32 v54, 6, v252
	v_lshrrev_b32_e32 v55, 1, v54
	v_and_b32_e32 v56, 1, v54
	v_and_b32_e32 v57, 63, v252
	v_lshrrev_b32_e32 v50, 2, v57
	v_lshl_add_u32 v50, v55, 4, v50
	v_lshlrev_b32_e32 v50, 13, v50
	v_and_b32_e32 v51, 3, v57
	v_lshlrev_b32_e32 v51, 4, v51
	v_bfe_u32 v52, v57, 5, 1
	v_lshlrev_b32_e32 v52, 5, v52
	v_xor_b32_e32 v51, v51, v52
	v_or_b32_e32 v50, v50, v51
	v_lshl_add_u32 v50, v56, 7, v50
	v_add_u32_e32 v51, 64, v50
	v_add_u32_e32 v52, 0x100, v50
	v_add_u32_e32 v53, 0x140, v50
	v_lshlrev_b32_e32 v29, 13, v55
	v_lshl_add_u32 v29, v56, 11, v29
	s_nop 0
	v_readfirstlane_b32 s100, v29
	v_readfirstlane_b32 s5, v29
	v_add_u32_e32 v6, 0x8000, v29
	s_add_u32 s84, s9, s46
	s_mov_b32 m0, s5
	v_readfirstlane_b32 s5, v6
	v_or_b32_e32 v6, 0x400, v29
	s_addc_u32 s85, s31, s47
	global_load_lds_dwordx4 v50, s[50:51]
	s_mov_b32 m0, s5
	v_readfirstlane_b32 s5, v6
	v_add_u32_e32 v6, 0x8400, v29
	global_load_lds_dwordx4 v50, s[84:85]
	s_mov_b32 m0, s5
	v_readfirstlane_b32 s5, v6
	v_add_u32_e32 v6, 0x1000, v29
	global_load_lds_dwordx4 v51, s[50:51]
	s_mov_b32 m0, s5
	v_readfirstlane_b32 s5, v6
	v_add_u32_e32 v6, 0x9000, v29
	global_load_lds_dwordx4 v51, s[84:85]
	s_mov_b32 m0, s5
	v_readfirstlane_b32 s5, v6
	v_add_u32_e32 v6, 0x1400, v29
	global_load_lds_dwordx4 v52, s[50:51]
	s_mov_b32 m0, s5
	v_readfirstlane_b32 s5, v6
	v_add_u32_e32 v6, 0x9400, v29
	global_load_lds_dwordx4 v52, s[84:85]
	s_mov_b32 m0, s5
	v_readfirstlane_b32 s5, v6
	global_load_lds_dwordx4 v53, s[50:51]
	s_mov_b32 m0, s5
	v_and_b32_e32 v6, 48, v1
	global_load_lds_dwordx4 v53, s[84:85]
	v_ashrrev_i32_e32 v1, 3, v24
	v_lshlrev_b32_e32 v0, 4, v0
	v_and_b32_e32 v25, 15, v24
	v_and_b32_e32 v1, 0xffffffe0, v1
	v_lshlrev_b32_e32 v9, 2, v24
	v_and_b32_e32 v28, 48, v0
	v_mul_i32_i24_e32 v0, 0x1fe00, v8
	v_or_b32_e32 v26, v1, v25
	v_and_b32_e32 v2, 48, v24
	v_lshlrev_b32_e32 v7, 6, v25
	v_and_b32_e32 v9, 32, v9
	v_lshlrev_b32_e32 v32, 9, v1
	v_bitop3_b32 v0, v6, v0, v4 bitop3:0xde
	v_lshlrev_b32_e32 v1, 6, v3
	v_bitop3_b32 v30, v7, v9, v2 bitop3:0x36
	v_add3_u32 v192, v0, v5, v1
	v_mul_i32_i24_e32 v0, 0x1fe00, v11
	v_mul_i32_i24_e32 v2, 0x1fe00, v14
	v_mul_i32_i24_e32 v7, 0x1fe00, v16
	s_add_u32 s42, s8, s42
	v_bitop3_b32 v0, v6, v0, v4 bitop3:0xde
	v_lshlrev_b32_e32 v1, 6, v10
	v_bitop3_b32 v2, v6, v2, v4 bitop3:0xde
	v_lshlrev_b32_e32 v3, 6, v12
	v_bitop3_b32 v4, v6, v7, v4 bitop3:0xde
	v_lshlrev_b32_e32 v6, 6, v15
	s_addc_u32 s43, s12, s43
	v_add3_u32 v0, v0, v5, v1
	v_mov_b32_e32 v1, v193
	v_add3_u32 v2, v2, v5, v3
	v_mov_b32_e32 v3, v193
	v_add3_u32 v4, v4, v5, v6
	v_mov_b32_e32 v5, v193
	v_mov_b32_e32 v192, v50
	v_mov_b32_e32 v0, v51
	v_mov_b32_e32 v2, v52
	v_mov_b32_e32 v4, v53
	v_lshl_add_u64 v[8:9], s[42:43], 0, v[192:193]
	v_lshl_add_u64 v[10:11], s[42:43], 0, v[0:1]
	v_lshl_add_u64 v[12:13], s[42:43], 0, v[2:3]
	v_lshl_add_u64 v[14:15], s[42:43], 0, v[4:5]
	s_add_u32 s42, s10, s46
	s_waitcnt vmcnt(0)
	s_addc_u32 s43, s11, s47
	v_lshl_add_u64 v[18:19], s[42:43], 0, v[0:1]
	v_mov_b32_e32 v0, 0
	v_and_b32_e32 v27, 63, v24
	v_lshlrev_b32_e32 v31, 9, v28
	v_lshl_add_u64 v[16:17], s[42:43], 0, v[192:193]
	v_lshl_add_u64 v[20:21], s[42:43], 0, v[2:3]
	v_lshl_add_u64 v[22:23], s[42:43], 0, v[4:5]
	s_mov_b32 s5, 0
	s_mov_b64 s[42:43], 0
	v_mov_b32_e32 v1, v0
	v_mov_b32_e32 v2, v0
	v_mov_b32_e32 v3, v0
	v_mov_b32_e32 v4, v0
	v_mov_b32_e32 v5, v0
	v_mov_b32_e32 v6, v0
	v_mov_b32_e32 v7, v0
	s_waitcnt vmcnt(0) lgkmcnt(0)
	s_barrier
	s_add_u32 s101, s100, 0x10000
	s_add_u32 m0, s101, 0x0
	s_nop 0
	global_load_lds_dwordx4 v[8:9], off
	s_add_u32 m0, s101, 0x8000
	s_nop 0
	global_load_lds_dwordx4 v[16:17], off
	s_add_u32 m0, s101, 0x400
	s_nop 0
	global_load_lds_dwordx4 v[10:11], off
	s_add_u32 m0, s101, 0x8400
	s_nop 0
	global_load_lds_dwordx4 v[18:19], off
; #define LDSP __attribute__((address_space(3)))
; #define WAIT_V0() asm volatile("s_waitcnt vmcnt(0)" ::: "memory")
; template <int EK, int TS, int KS>
; DI void ctx_tiles(const Params& p, int l, const bf16_t* __restrict__ A, const bf16_t* __restrict__ Bt, int N, int K, ldsp_t shm) {
;     ...
;         for (int t = 0; t < nt; ++t) {
;             const int cur = t & 1;
;             if (t + 1 < nt) C_STAGE(cur ^ 1, t + 1);
;             ldsp_t sa = shm + cur * 2 * TILE_A, sb = sa + TILE_A;
; #pragma unroll
;             for (int ks = 0; ks < KS; ++ks) {
;                 bf16x8 At[MT], Bf[NT];
; #pragma unroll
;                 for (int m = 0; m < MT; ++m) At[m] = *(const LDSP bf16x8*)(sa + aoff + m * (KS * 1024) + ks * 1024);
; #pragma unroll
;                 for (int n = 0; n < NT; ++n) Bf[n] = *(const LDSP bf16x8*)(sb + boff + n * (KS * 1024) + ks * 1024);
; #pragma unroll
;                 for (int m = 0; m < MT; ++m)
; #pragma unroll
;                     for (int n = 0; n < NT; ++n) acc[m][n] = __builtin_amdgcn_mfma_f32_16x16x32_bf16(Bf[n], At[m], acc[m][n], 0, 0, 0);
;             }
;             WAIT_V0(); __syncthreads();
;         }
.LBB0_247:
	s_and_b32 s45, s5, 0x10000
	s_xor_b32 s46, s45, 0x10000
	s_add_u32 s101, s100, s46
	v_lshl_add_u64 v[34:35], v[12:13], 0, s[42:43]
	s_add_u32 m0, s101, 0x1000
	s_nop 0
	global_load_lds_dwordx4 v[34:35], off
	v_lshl_add_u64 v[34:35], v[20:21], 0, s[42:43]
	s_add_u32 m0, s101, 0x9000
	s_nop 0
	global_load_lds_dwordx4 v[34:35], off
	v_lshl_add_u64 v[34:35], v[14:15], 0, s[42:43]
	s_add_u32 m0, s101, 0x1400
	s_nop 0
	global_load_lds_dwordx4 v[34:35], off
	v_lshl_add_u64 v[34:35], v[22:23], 0, s[42:43]
	s_add_u32 m0, s101, 0x9400
	s_nop 0
	global_load_lds_dwordx4 v[34:35], off
	v_or_b32_e32 v33, s45, v30
	v_add_u32_e32 v46, v33, v32
	v_add_u32_e32 v33, v33, v31
	ds_read_b128 v[34:37], v46
	ds_read_b128 v[38:41], v46 offset:8192
	ds_read_b128 v[42:45], v33 offset:32768
	s_waitcnt lgkmcnt(0)
	v_mfma_f32_16x16x32_bf16 v[0:3], v[42:45], v[34:37], v[0:3]
	v_mfma_f32_16x16x32_bf16 v[4:7], v[42:45], v[38:41], v[4:7]
	ds_read_b128 v[34:37], v46 offset:1024
	ds_read_b128 v[38:41], v46 offset:9216
	ds_read_b128 v[42:45], v33 offset:33792
	s_waitcnt lgkmcnt(0)
	v_mfma_f32_16x16x32_bf16 v[0:3], v[42:45], v[34:37], v[0:3]
	v_mfma_f32_16x16x32_bf16 v[4:7], v[42:45], v[38:41], v[4:7]
	ds_read_b128 v[34:37], v46 offset:2048
	ds_read_b128 v[38:41], v46 offset:10240
	ds_read_b128 v[42:45], v33 offset:34816
	s_waitcnt lgkmcnt(0)
	v_mfma_f32_16x16x32_bf16 v[0:3], v[42:45], v[34:37], v[0:3]
	v_mfma_f32_16x16x32_bf16 v[4:7], v[42:45], v[38:41], v[4:7]
	ds_read_b128 v[34:37], v46 offset:3072
	ds_read_b128 v[38:41], v46 offset:11264
	ds_read_b128 v[42:45], v33 offset:35840
	s_waitcnt lgkmcnt(0)
	v_mfma_f32_16x16x32_bf16 v[0:3], v[42:45], v[34:37], v[0:3]
	v_mfma_f32_16x16x32_bf16 v[4:7], v[42:45], v[38:41], v[4:7]
	s_waitcnt vmcnt(8)
	s_barrier
	s_cmpk_eq_i32 s42, 0x1c00
	s_cbranch_scc1 .Lctxring_skip
	s_add_u32 s101, s100, s45
	s_add_u32 s46, s42, 0x200
	s_addc_u32 s47, s43, 0
	v_lshl_add_u64 v[34:35], v[8:9], 0, s[46:47]
	s_add_u32 m0, s101, 0x0
	s_nop 0
	global_load_lds_dwordx4 v[34:35], off
	v_lshl_add_u64 v[34:35], v[16:17], 0, s[46:47]
	s_add_u32 m0, s101, 0x8000
	s_nop 0
	global_load_lds_dwordx4 v[34:35], off
	v_lshl_add_u64 v[34:35], v[10:11], 0, s[46:47]
	s_add_u32 m0, s101, 0x400
	s_nop 0
	global_load_lds_dwordx4 v[34:35], off
	v_lshl_add_u64 v[34:35], v[18:19], 0, s[46:47]
	s_add_u32 m0, s101, 0x8400
	s_nop 0
	global_load_lds_dwordx4 v[34:35], off
.Lctxring_skip:
	ds_read_b128 v[34:37], v46 offset:4096
	ds_read_b128 v[38:41], v46 offset:12288
	ds_read_b128 v[42:45], v33 offset:36864
	s_waitcnt lgkmcnt(0)
	v_mfma_f32_16x16x32_bf16 v[0:3], v[42:45], v[34:37], v[0:3]
	v_mfma_f32_16x16x32_bf16 v[4:7], v[42:45], v[38:41], v[4:7]
	ds_read_b128 v[34:37], v46 offset:5120
	ds_read_b128 v[38:41], v46 offset:13312
	ds_read_b128 v[42:45], v33 offset:37888
	s_waitcnt lgkmcnt(0)
	v_mfma_f32_16x16x32_bf16 v[0:3], v[42:45], v[34:37], v[0:3]
	v_mfma_f32_16x16x32_bf16 v[4:7], v[42:45], v[38:41], v[4:7]
	ds_read_b128 v[34:37], v46 offset:6144
	ds_read_b128 v[38:41], v46 offset:14336
	ds_read_b128 v[42:45], v33 offset:38912
	s_waitcnt lgkmcnt(0)
	v_mfma_f32_16x16x32_bf16 v[0:3], v[42:45], v[34:37], v[0:3]
	v_mfma_f32_16x16x32_bf16 v[4:7], v[42:45], v[38:41], v[4:7]
	ds_read_b128 v[34:37], v46 offset:7168
	ds_read_b128 v[38:41], v46 offset:15360
	ds_read_b128 v[42:45], v33 offset:39936
	s_waitcnt lgkmcnt(0)
	v_mfma_f32_16x16x32_bf16 v[0:3], v[42:45], v[34:37], v[0:3]
	v_mfma_f32_16x16x32_bf16 v[4:7], v[42:45], v[38:41], v[4:7]
	s_add_i32 s5, s5, 0x10000
	s_add_u32 s42, s42, 0x200
	s_addc_u32 s43, s43, 0
	s_cmpk_eq_i32 s42, 0x1e00
	s_waitcnt vmcnt(8)
	s_barrier
	s_cbranch_scc0 .LBB0_247
	s_waitcnt vmcnt(0)
	s_barrier
	v_add3_u32 v29, v32, v30, s13
	v_add3_u32 v30, v31, v30, s30
	ds_read_b128 v[8:11], v29 offset:1024
	ds_read_b128 v[12:15], v30
	ds_read_b128 v[16:19], v29 offset:8192
	ds_read_b128 v[20:23], v29
	s_waitcnt lgkmcnt(1)
	v_mfma_f32_16x16x32_bf16 v[4:7], v[12:15], v[16:19], v[4:7]
	s_waitcnt lgkmcnt(0)
	v_mfma_f32_16x16x32_bf16 v[0:3], v[12:15], v[20:23], v[0:3]
	ds_read_b128 v[12:15], v29 offset:9216
	ds_read_b128 v[16:19], v30 offset:1024
	s_waitcnt lgkmcnt(0)
	v_mfma_f32_16x16x32_bf16 v[0:3], v[16:19], v[8:11], v[0:3]
	v_mfma_f32_16x16x32_bf16 v[4:7], v[16:19], v[12:15], v[4:7]
	ds_read_b128 v[8:11], v29 offset:2048
	ds_read_b128 v[12:15], v29 offset:10240
	ds_read_b128 v[16:19], v30 offset:2048
	s_waitcnt lgkmcnt(0)
	v_mfma_f32_16x16x32_bf16 v[0:3], v[16:19], v[8:11], v[0:3]
	v_mfma_f32_16x16x32_bf16 v[4:7], v[16:19], v[12:15], v[4:7]
	ds_read_b128 v[8:11], v29 offset:3072
	ds_read_b128 v[12:15], v29 offset:11264
	ds_read_b128 v[16:19], v30 offset:3072
	s_waitcnt lgkmcnt(0)
	v_mfma_f32_16x16x32_bf16 v[0:3], v[16:19], v[8:11], v[0:3]
	v_mfma_f32_16x16x32_bf16 v[4:7], v[16:19], v[12:15], v[4:7]
	ds_read_b128 v[8:11], v29 offset:4096
	ds_read_b128 v[12:15], v29 offset:12288
	ds_read_b128 v[16:19], v30 offset:4096
	s_waitcnt lgkmcnt(0)
	v_mfma_f32_16x16x32_bf16 v[0:3], v[16:19], v[8:11], v[0:3]
	v_mfma_f32_16x16x32_bf16 v[4:7], v[16:19], v[12:15], v[4:7]
	ds_read_b128 v[8:11], v29 offset:5120
	ds_read_b128 v[12:15], v29 offset:13312
	ds_read_b128 v[16:19], v30 offset:5120
	s_waitcnt lgkmcnt(0)
	v_mfma_f32_16x16x32_bf16 v[0:3], v[16:19], v[8:11], v[0:3]
	v_mfma_f32_16x16x32_bf16 v[4:7], v[16:19], v[12:15], v[4:7]
	ds_read_b128 v[8:11], v29 offset:6144
	ds_read_b128 v[12:15], v29 offset:14336
	ds_read_b128 v[16:19], v30 offset:6144
	s_waitcnt lgkmcnt(0)
	v_mfma_f32_16x16x32_bf16 v[0:3], v[16:19], v[8:11], v[0:3]
	v_mfma_f32_16x16x32_bf16 v[4:7], v[16:19], v[12:15], v[4:7]
	ds_read_b128 v[8:11], v29 offset:7168
	ds_read_b128 v[12:15], v29 offset:15360
	ds_read_b128 v[16:19], v30 offset:7168
	s_waitcnt vmcnt(0)
	s_waitcnt lgkmcnt(0)
	v_mfma_f32_16x16x32_bf16 v[0:3], v[16:19], v[8:11], v[0:3]
	v_lshrrev_b32_e32 v8, 4, v27
	v_lshrrev_b32_e32 v9, 2, v28
	v_bitop3_b32 v8, v9, v25, v8 bitop3:0x36
	v_mfma_f32_16x16x32_bf16 v[4:7], v[16:19], v[12:15], v[4:7]
	v_lshlrev_b32_e32 v9, 8, v26
	v_lshl_or_b32 v8, v8, 4, v9
	s_barrier
; #define LDSP __attribute__((address_space(3)))
; template <int EK>
; DI void ctx_item(const Params& p, int l, int grow, int gcol, int slot, f32x4 s0, f32x4 s1, bool lead) {
;     ...
;         const float* gate = p.mod + ((size_t)l * 5 + 4) * 6144 + (EK == 1 ? 2 : 5) * DM + gcol;
;         float* xr = p.xc + (size_t)grow * DM + gcol;
;         const float* xs = (EK == 1 && l == 0) ? p.ctx + (size_t)grow * DM + gcol : xr;
;         const f32x4 g0 = *(const f32x4*)gate, g1 = *(const f32x4*)(gate + 4);
;         f32x4 x0 = *(const f32x4*)xs, x1 = *(const f32x4*)(xs + 4);
;         x0 += g0 * s0; x1 += g1 * s1;
;         *(f32x4*)xr = x0; *(f32x4*)(xr + 4) = x1;
;         const int ln = EK == 1 ? l : l + 1;
;         const float* gnx = (EK == 1 ? p.norm2_g : p.norm1_g) + (size_t)ln * DM + gcol;
;         const float* scn = p.mod + ((size_t)ln * 5 + 4) * 6144 + (EK == 1 ? 4 : 1) * DM + gcol;
;         const f32x4 a0 = *(const f32x4*)gnx * (1.f + *(const f32x4*)scn), a1 = *(const f32x4*)(gnx + 4) * (1.f + *(const f32x4*)(scn + 4));
;         const f32x4 y0 = x0 * a0, y1 = x1 * a1;
;         u32x4 w; w[0] = pk2(y0[0], y0[1]); w[1] = pk2(y0[2], y0[3]); w[2] = pk2(y1[0], y1[1]); w[3] = pk2(y1[2], y1[3]);
;         *(u32x4*)(p.H + (size_t)(NLAT + grow) * DM + gcol) = w;
; template <int EK, int TS, int KS>
; DI void ctx_tiles(const Params& p, int l, const bf16_t* __restrict__ A, const bf16_t* __restrict__ Bt, int N, int K, ldsp_t shm) {
;     ...
; #pragma unroll
;         for (int m = 0; m < MT; ++m)
; #pragma unroll
;             for (int n = 0; n < NT; ++n) {
;                 const int row = wr * WM + m * 16 + fr, ch = (wc * WN + n * 16 + fq * 4) >> 2;
;                 *(LDSP f32x4*)(shm + row * (TS * 4) + ((ch ^ (row & 15)) << 4)) = acc[m][n];
;             }
;         __syncthreads();
; #pragma unroll
;         for (int it = 0; it < (TS * TS / 8) / 512; ++it) {
;             const int item = it * 512 + tid, row = item / (TS / 8), c8 = item % (TS / 8);
;             const f32x4 s0 = *(const LDSP f32x4*)(shm + row * (TS * 4) + (((2 * c8) ^ (row & 15)) << 4));
;             const f32x4 s1 = *(const LDSP f32x4*)(shm + row * (TS * 4) + (((2 * c8 + 1) ^ (row & 15)) << 4));
;             ctx_item<EK>(p, l, tm * TS + row, tn * TS + c8 * 8, tn, s0, s1, c8 == 0);
;         }
;         __syncthreads();
	s_nop 0
	ds_write_b128 v8, v[0:3]
	s_nop 2
	ds_write_b128 v8, v[4:7] offset:4096
	v_ashrrev_i32_e32 v0, 31, v24
	v_lshrrev_b32_e32 v0, 29, v0
	v_add_u32_e32 v0, v24, v0
	v_ashrrev_i32_e32 v1, 3, v0
	v_and_b32_e32 v0, -8, v0
	v_sub_u32_e32 v0, v24, v0
	v_lshlrev_b32_e32 v3, 1, v0
	v_and_b32_e32 v4, 15, v1
	v_bitop3_b32 v5, v3, v1, 15 bitop3:0x78
	v_bitop3_b32 v3, v3, v4, 1 bitop3:0x36
	v_lshl_add_u32 v4, s4, 6, v1
	s_lshl_b32 s4, s40, 6
	v_lshl_add_u32 v26, v0, 3, s4
	v_cmp_lt_i32_e64 s[4:5], v134, v203
	v_cmp_eq_u32_e32 vcc, 0, v0
	v_lshlrev_b32_e32 v2, 8, v1
	v_cndmask_b32_e64 v0, v202, v134, s[4:5]
	v_cmp_lt_i32_e64 s[4:5], v135, v203
	v_lshlrev_b32_e32 v34, 2, v0
	v_lshl_add_u32 v6, v5, 4, v2
	v_cndmask_b32_e64 v0, v202, v135, s[4:5]
	v_ashrrev_i32_e32 v27, 31, v26
	v_ashrrev_i32_e32 v5, 31, v4
	v_lshlrev_b32_e32 v35, 2, v0
	v_xor_b32_e32 v0, 4, v202
	v_lshlrev_b64 v[10:11], 12, v[4:5]
	v_cmp_lt_i32_e64 s[4:5], v0, v203
	v_lshlrev_b64 v[30:31], 2, v[26:27]
	v_lshl_add_u32 v7, v3, 4, v2
	v_cndmask_b32_e64 v0, v202, v0, s[4:5]
	v_lshl_add_u64 v[14:15], s[34:35], 0, v[30:31]
	v_lshl_add_u64 v[10:11], s[70:71], 0, v[10:11]
	s_waitcnt lgkmcnt(0)
	s_barrier
	v_lshlrev_b32_e32 v36, 2, v0
	ds_read_b128 v[0:3], v6
	ds_read_b128 v[6:9], v7
	v_lshl_add_u64 v[32:33], v[10:11], 0, v[30:31]
	global_load_dwordx4 v[10:13], v[14:15], off offset:16
	s_nop 0
	global_load_dwordx4 v[14:17], v[14:15], off
	s_nop 0
	global_load_dwordx4 v[18:21], v[32:33], off offset:16
	global_load_dwordx4 v[22:25], v[32:33], off
	v_lshlrev_b64 v[28:29], 11, v[4:5]
	s_waitcnt vmcnt(0) lgkmcnt(1)
	v_pk_fma_f32 v[16:17], v[2:3], v[16:17], v[24:25]
	v_pk_fma_f32 v[14:15], v[0:1], v[14:15], v[22:23]
	s_waitcnt lgkmcnt(0)
	v_pk_fma_f32 v[2:3], v[8:9], v[12:13], v[20:21]
	v_pk_fma_f32 v[0:1], v[6:7], v[10:11], v[18:19]
	global_store_dwordx4 v[32:33], v[14:17], off
	global_store_dwordx4 v[32:33], v[0:3], off offset:16
	v_lshl_add_u64 v[10:11], s[36:37], 0, v[30:31]
	v_lshl_add_u64 v[22:23], s[38:39], 0, v[30:31]
	global_load_dwordx4 v[6:9], v[10:11], off offset:16
	s_nop 0
	global_load_dwordx4 v[10:13], v[10:11], off
	s_nop 0
	global_load_dwordx4 v[18:21], v[22:23], off offset:16
	s_nop 0
	global_load_dwordx4 v[22:25], v[22:23], off
	s_waitcnt vmcnt(1)
	v_pk_add_f32 v[20:21], v[20:21], 1.0 op_sel_hi:[1,0]
	s_waitcnt vmcnt(0)
	v_pk_add_f32 v[22:23], v[22:23], 1.0 op_sel_hi:[1,0]
	v_pk_add_f32 v[18:19], v[18:19], 1.0 op_sel_hi:[1,0]
	v_pk_mul_f32 v[10:11], v[10:11], v[22:23]
	v_pk_mul_f32 v[8:9], v[8:9], v[20:21]
	v_pk_mul_f32 v[6:7], v[6:7], v[18:19]
	v_pk_mul_f32 v[10:11], v[14:15], v[10:11]
	v_pk_add_f32 v[24:25], v[24:25], 1.0 op_sel_hi:[1,0]
	v_pk_mul_f32 v[18:19], v[2:3], v[8:9]
	v_pk_mul_f32 v[8:9], v[0:1], v[6:7]
	v_cvt_pk_bf16_f32 v6, v10, v11
	v_lshl_add_u64 v[10:11], s[82:83], 0, v[28:29]
	v_pk_mul_f32 v[12:13], v[12:13], v[24:25]
	v_lshl_add_u64 v[10:11], v[26:27], 1, v[10:11]
	v_pk_mul_f32 v[12:13], v[16:17], v[12:13]
	v_add_co_u32_e64 v10, s[4:5], s14, v10
	v_cvt_pk_bf16_f32 v7, v12, v13
	v_cvt_pk_bf16_f32 v8, v8, v9
	v_cvt_pk_bf16_f32 v9, v18, v19
	v_addc_co_u32_e64 v11, s[4:5], 0, v11, s[4:5]
	global_store_dwordx4 v[10:11], v[6:9], off
	s_nop 1
	v_mul_f32_e32 v6, v15, v15
	v_fmac_f32_e32 v6, v14, v14
	v_fmac_f32_e32 v6, v16, v16
	v_fmac_f32_e32 v6, v17, v17
	v_fmac_f32_e32 v6, v0, v0
	v_fmac_f32_e32 v6, v1, v1
	v_fmac_f32_e32 v6, v2, v2
	v_fmac_f32_e32 v6, v3, v3
	ds_bpermute_b32 v0, v34, v6
	s_waitcnt lgkmcnt(0)
	v_add_f32_e32 v0, v6, v0
	ds_bpermute_b32 v1, v35, v0
	s_waitcnt lgkmcnt(0)
	v_add_f32_e32 v0, v0, v1
	ds_bpermute_b32 v1, v36, v0
	s_and_saveexec_b64 s[4:5], vcc
	s_cbranch_execz .LBB0_245
	v_lshl_add_u64 v[2:3], s[6:7], 0, v[4:5]
	v_lshlrev_b64 v[2:3], 6, v[2:3]
	v_lshl_add_u64 v[2:3], s[74:75], 0, v[2:3]
	v_lshl_add_u64 v[2:3], s[40:41], 2, v[2:3]
	s_waitcnt lgkmcnt(0)
	v_add_f32_e32 v0, v0, v1
	global_store_dword v[2:3], v0, off
	s_branch .LBB0_245
